# P4 gather: saddr-form loads (per-item SGPR base + 32-bit key*512+lane offset via sdwa shift + add3) instead of two 64-bit VALU adds per row pair
# baseline (speedup 1.0000x reference)
; __device__ __forceinline__ void p4_attn(const Params& p, unsigned char* lds, int bid, int nb, bool dry) {
;   LAS unsigned char* cbuf = (LAS unsigned char*)lds;
;   LAS float* biasd = (LAS float*)((LAS unsigned char*)lds + 2 * CBUF);
;   LAS unsigned short* idxs = (LAS unsigned short*)((LAS unsigned char*)lds + 2 * CBUF + 129 * 32 * 4);
;   const bf16_t* ckvn = (const bf16_t*)(p.ws + OFF_CKVN); const unsigned short* idxg = (const unsigned short*)(p.ws + OFF_IDX);
;   unsigned char* QL = p.ws + OFF_QL0;
;   int tid = threadIdx.x; asm volatile("" : "+v"(tid));
;   const int lane = tid & 63, wid = __builtin_amdgcn_readfirstlane(tid >> 6), g = lane >> 4, r16 = lane & 15;
;   for (int i = tid; i < 129 * 32; i += 512) {
;     const int d = i >> 5, hd = i & 31; int bucket = d;
;     if (d >= 16) { bucket = 16 + (d >= 19) + (d >= 21) + (d >= 24) + (d >= 27) + (d >= 31) + (d >= 35) + (d >= 40) + (d >= 46) + (d >= 52) + (d >= 59) + (d >= 67) + (d >= 77) + (d >= 87) + (d >= 99) + (d >= 113); }
;     biasd[i] = ((const float*)(p.ws + OFF_SMALL))[SM_RELB + bucket * 32 + hd] * LOG2E;
;   }
;   LAS unsigned* pcnt = (LAS unsigned*)((LAS unsigned char*)lds + 2 * CBUF + 129 * 32 * 4 + 2048) + (wid >> 1);
;   if (tid < 4) ((LAS unsigned*)((LAS unsigned char*)lds + 2 * CBUF + 129 * 32 * 4 + 2048))[tid] = 0u;
;   __syncthreads();
;   unsigned epoch = 0u;
;   const int tok = wid >> 1, hw = wid & 1, head = hw * 16 + r16;
;   const float SC = 0.08838834764831845f * LOG2E;
;   const int qoff = 16 * (g ^ (r16 >> 3));
;   const int q4 = r16 >> 2, pp = r16 & 3;
;   const int troff = (4 * g + q4) * CROW + 16 * ((pp >> 1) ^ (g >> 1)) + 8 * (pp & 1);
;   const int wrow = 16 * hw + 8 * (lane >> 5), wch = lane & 31;
;   for (int round = 0; round * nb < T / 4; ++round) {
;     const int item = round * nb + (bid + round * 37) % nb;
;     const int tg0 = item * 4, b = tg0 >> 11, t0 = tg0 & 2047, t = t0 + tok, tg = tg0 + tok;
;     const int nk = min(t + 1, 256), nkmax = min(t0 + 4, 256), nch = (nkmax + 31) >> 5;
;     ((LAS unsigned*)idxs)[tid] = ((const unsigned*)(idxg + (size_t)tg0 * 256))[tid];
;     unsigned char* qrow = QL + (size_t)tg * 8192 + head * 256;
;     bf16x8 qB[8];
; #pragma unroll
;     for (int s = 0; s < 8; ++s) { const u32x2 qw = *(const u32x2*)(qrow + 32 * s + 8 * g);
;       typedef float f32x2v __attribute__((ext_vector_type(2)));
.LBB0_988:
	s_or_b64 exec, exec, s[4:5]
	v_cmp_gt_i32_e32 vcc, 4, v2
	s_and_saveexec_b64 s[4:5], vcc
	v_add_u32_e32 v0, 0x26880, v0
	v_mov_b32_e32 v1, 0
	ds_write_b32 v0, v1
	s_or_b64 exec, exec, s[4:5]
	v_bfe_u32 v5, v2, 4, 2
	v_bfe_u32 v0, v2, 3, 1
	v_mov_b32_e32 v0, v5
	v_lshlrev_b32_e32 v162, 4, v0
	v_bfe_u32 v0, v2, 2, 2
	v_lshlrev_b32_e32 v148, 2, v5
	v_or_b32_e32 v0, v148, v0
	s_ashr_i32 s0, s3, 7
	s_lshr_b32 s3, s3, 2
	v_mul_u32_u24_e32 v163, 0x220, v0
	v_lshrrev_b32_e32 v0, 1, v2
	v_bfe_u32 v8, v2, 5, 1
	v_and_b32_e32 v6, 15, v2
	s_and_b32 s3, s3, 16
	v_and_b32_e32 v0, 1, v0
	v_readlane_b32 s4, v254, 36
	v_or_b32_e32 v7, s3, v6
	v_lshlrev_b32_e32 v164, 4, v0
	v_lshlrev_b32_e32 v0, 3, v2
	v_ashrrev_i32_e32 v3, 31, v2
	v_readlane_b32 s5, v254, 37
	v_and_b32_e32 v165, 8, v0
	v_and_b32_e32 v10, 31, v2
	v_lshl_add_u64 v[150:151], v[2:3], 2, s[4:5]
	v_lshlrev_b32_e32 v0, 8, v7
	v_mov_b32_e32 v1, 0
	v_readlane_b32 s4, v254, 42
	v_lshl_add_u64 v[152:153], s[92:93], 0, v[0:1]
	v_lshlrev_b32_e32 v0, 4, v10
	v_readlane_b32 s5, v254, 43
	v_lshl_or_b32 v9, v8, 3, s3
	s_add_i32 s3, 0, 0x26080
	v_lshl_add_u64 v[156:157], s[4:5], 0, v[0:1]
	s_sub_i32 s42, 0, s4
	s_lshl_b32 s4, s0, 9
	s_lshl_b32 s2, s0, 2
	v_lshl_add_u32 v166, v2, 2, s3
	s_add_i32 s3, s3, s4
	s_mul_i32 s4, s0, 0x4400
	v_and_b32_e32 v0, 31, v2
	s_add_i32 s2, s2, 0
	v_and_b32_e32 v4, 63, v2
	s_add_i32 s5, s4, 0
	v_lshlrev_b32_e32 v0, 4, v0
	s_add_i32 s4, 0, 0x22000
	v_mul_u32_u24_e32 v2, 0x220, v9
	s_mov_b32 s1, 0
	s_add_i32 s2, s2, 0x26880
	v_lshlrev_b32_e32 v154, 3, v5
	v_mov_b32_e32 v155, v1
	v_cmp_eq_u32_e64 s[8:9], 0, v4
	v_lshl_add_u32 v167, v9, 1, s3
	v_mul_u32_u24_e32 v168, 0x220, v6
	v_lshl_add_u32 v169, v7, 2, s4
	v_mov_b32_e32 v149, v1
	v_add3_u32 v170, s5, v0, v2
	s_movk_i32 s16, 0x80
	s_mov_b32 s4, 0x3e0293ee
	s_mov_b32 s17, 0xf149f2ca
	s_mov_b32 s18, 0x41800000
	v_mov_b32_e32 v171, 9
	v_mov_b32_e32 v172, 0x80
	v_mov_b32_e32 v173, 0xf149f2ca
	s_mov_b32 s10, 0
	s_mov_b32 s19, 0
	s_mov_b32 s20, 0
	s_lshl_b32 s28, s88, 11
	s_mov_b32 s29, 0
	v_lshl_add_u64 v[2:3], v[150:151], 0, s[28:29]
	global_load_dword v255, v[2:3], off
	s_lshl_b32 s28, s88, 2
	s_add_i32 s28, s28, s0
	s_lshl_b32 s28, s28, 13
	v_lshl_add_u64 v[194:195], v[152:153], 0, s[28:29]
	v_lshl_add_u64 v[194:195], v[194:195], 0, v[154:155]
	global_load_dwordx2 v[218:219], v[194:195], off
	global_load_dwordx2 v[220:221], v[194:195], off offset:32
	global_load_dwordx2 v[222:223], v[194:195], off offset:64
	global_load_dwordx2 v[224:225], v[194:195], off offset:96
	global_load_dwordx2 v[226:227], v[194:195], off offset:128
	global_load_dwordx2 v[228:229], v[194:195], off offset:160
	global_load_dwordx2 v[230:231], v[194:195], off offset:192
	global_load_dwordx2 v[232:233], v[194:195], off offset:224
	s_waitcnt vmcnt(0)
	s_waitcnt lgkmcnt(0)
	s_barrier

; #define LAS __attribute__((address_space(3)))
; __device__ __forceinline__ unsigned cvt_pk_bf16(float lo, float hi) { unsigned r; asm("v_cvt_pk_bf16_f32 %0, %1, %2" : "=v"(r) : "v"(lo), "v"(hi)); return r; }
; #define P4_LOAD(ch) do { const u32x4 kk_ = *(const LAS u32x4*)(idxs + tok * 256 + (ch) * 32 + wrow); \
;       _Pragma("unroll") for (int i = 0; i < 8; ++i) { \
;       const int key = (int)((kk_[i >> 1] >> (16 * (i & 1))) & 0xffffu); stg[i] = *(const u32x4*)(cbase + (size_t)key * 256); } } while (0)
; #define P4_WRITE(bufp) do { _Pragma("unroll") for (int i = 0; i < 8; ++i) \
;       *(LAS u32x4*)((bufp) + (wrow + i) * CROW + 16 * (wch ^ (lane >> 5))) = stg[i]; } while (0)
; __device__ __forceinline__ void p4_attn(const Params& p, unsigned char* lds, int bid, int nb, bool dry) {
;     ...
;     const int item = round * nb + (bid + round * 37) % nb;
;     const int tg0 = item * 4, b = tg0 >> 11, t0 = tg0 & 2047, t = t0 + tok, tg = tg0 + tok;
;     const int nk = min(t + 1, 256), nkmax = min(t0 + 4, 256), nch = (nkmax + 31) >> 5;
;     ((LAS unsigned*)idxs)[tid] = ((const unsigned*)(idxg + (size_t)tg0 * 256))[tid];
;     unsigned char* qrow = QL + (size_t)tg * 8192 + head * 256;
;     bf16x8 qB[8];
; #pragma unroll
;     for (int s = 0; s < 8; ++s) { const u32x2 qw = *(const u32x2*)(qrow + 32 * s + 8 * g);
;       typedef float f32x2v __attribute__((ext_vector_type(2)));
;       const f32x2v a0 = __builtin_amdgcn_cvt_pk_f32_fp8(qw[0], false), a1 = __builtin_amdgcn_cvt_pk_f32_fp8(qw[0], true), a2 = __builtin_amdgcn_cvt_pk_f32_fp8(qw[1], false), a3 = __builtin_amdgcn_cvt_pk_f32_fp8(qw[1], true);
;       u32x4 pw; pw[0] = cvt_pk_bf16(a0[0], a0[1]); pw[1] = cvt_pk_bf16(a1[0], a1[1]); pw[2] = cvt_pk_bf16(a2[0], a2[1]); pw[3] = cvt_pk_bf16(a3[0], a3[1]);
;       union { u32x4 u; bf16x8 v; } cv; cv.u = pw; qB[s] = cv.v; }
;     epoch += 2u; pair_sync(pcnt, epoch, lane);
;     u32x4 stg[8];
;     const bf16_t* cbase = ckvn + (size_t)b * L * 256 + wch * 8;
;     ...
;     P4_LOAD(0);
;     P4_WRITE(cbuf + tok * CTOK);
.LBB0_996:
	ds_read_b128 v[36:39], v167
	s_ashr_i32 s12, s21, 9
	s_ashr_i32 s13, s12, 31
	s_lshl_b64 s[12:13], s[12:13], 20
	v_lshl_add_u64 v[160:161], v[156:157], 0, s[12:13]
	v_readlane_b32 s40, v254, 42
	v_readlane_b32 s41, v254, 43
	s_add_u32 s40, s40, s12
	s_addc_u32 s41, s41, s13
	s_waitcnt lgkmcnt(0)
	v_lshlrev_b32_e32 v0, 9, v36
	v_and_b32_e32 v0, 0x1fffe00, v0
	v_lshl_add_u64 v[2:3], v[160:161], 0, v[0:1]
	v_lshlrev_b32_sdwa v0, v171, v36 dst_sel:DWORD dst_unused:UNUSED_PAD src0_sel:DWORD src1_sel:WORD_1
	v_lshl_add_u64 v[40:41], v[160:161], 0, v[0:1]
	v_lshlrev_b32_e32 v0, 9, v37
	v_and_b32_e32 v0, 0x1fffe00, v0
	global_load_dwordx4 v[44:47], v[2:3], off
	global_load_dwordx4 v[48:51], v[40:41], off
	v_lshl_add_u64 v[2:3], v[160:161], 0, v[0:1]
	v_lshlrev_b32_sdwa v0, v171, v37 dst_sel:DWORD dst_unused:UNUSED_PAD src0_sel:DWORD src1_sel:WORD_1
	v_lshl_add_u64 v[36:37], v[160:161], 0, v[0:1]
	v_lshlrev_b32_e32 v0, 9, v38
	v_and_b32_e32 v0, 0x1fffe00, v0
	global_load_dwordx4 v[60:63], v[2:3], off
	global_load_dwordx4 v[68:71], v[36:37], off
	v_lshl_add_u64 v[2:3], v[160:161], 0, v[0:1]
	v_lshlrev_b32_sdwa v0, v171, v38 dst_sel:DWORD dst_unused:UNUSED_PAD src0_sel:DWORD src1_sel:WORD_1
	v_lshl_add_u64 v[36:37], v[160:161], 0, v[0:1]
	v_lshlrev_b32_e32 v0, 9, v39
	v_and_b32_e32 v0, 0x1fffe00, v0
	global_load_dwordx4 v[84:87], v[2:3], off
	global_load_dwordx4 v[88:91], v[36:37], off
	v_lshl_add_u64 v[2:3], v[160:161], 0, v[0:1]
	v_lshlrev_b32_sdwa v0, v171, v39 dst_sel:DWORD dst_unused:UNUSED_PAD src0_sel:DWORD src1_sel:WORD_1
	global_load_dwordx4 v[100:103], v[2:3], off
	v_lshl_add_u64 v[2:3], v[160:161], 0, v[0:1]
	global_load_dwordx4 v[108:111], v[2:3], off
	s_add_i32 s28, s20, 1
	s_mul_i32 s29, s28, s89
	s_mul_i32 s30, s28, 37
	s_add_i32 s30, s30, s88
	v_readlane_b32 s31, v254, 32
	s_mul_hi_u32 s31, s30, s31
	v_readlane_b32 s33, v254, 33
	s_mul_i32 s31, s31, s33
	s_sub_i32 s30, s30, s31
	s_sub_i32 s31, s30, s33
	s_cmp_ge_u32 s30, s33
	s_cselect_b32 s30, s31, s30
	s_sub_i32 s31, s30, s33
	s_cmp_ge_u32 s30, s33
	s_cselect_b32 s30, s31, s30
	s_add_i32 s30, s30, s29
	s_cmpk_gt_i32 s29, 0x1fff
	s_cselect_b32 s30, s21, s30
	s_mov_b32 s36, s30
	s_lshl_b32 s30, s30, 11
	s_mov_b32 s31, 0
	v_lshl_add_u64 v[2:3], v[150:151], 0, s[30:31]
	global_load_dword v255, v[2:3], off
	s_waitcnt vmcnt(20)
	v_cvt_pk_f32_fp8_e32 v[202:203], v218
	v_cvt_pk_f32_fp8_sdwa v[204:205], v218 src0_sel:WORD_1
	v_cvt_pk_f32_fp8_e32 v[206:207], v219
	v_cvt_pk_f32_fp8_sdwa v[208:209], v219 src0_sel:WORD_1
	v_cvt_pk_bf16_f32 v4, v202, v203
	v_cvt_pk_bf16_f32 v5, v204, v205
	v_cvt_pk_bf16_f32 v6, v206, v207
	v_cvt_pk_bf16_f32 v7, v208, v209
	s_waitcnt vmcnt(19)
	v_cvt_pk_f32_fp8_e32 v[210:211], v220
	v_cvt_pk_f32_fp8_sdwa v[212:213], v220 src0_sel:WORD_1
	v_cvt_pk_f32_fp8_e32 v[214:215], v221
	v_cvt_pk_f32_fp8_sdwa v[216:217], v221 src0_sel:WORD_1
	v_cvt_pk_bf16_f32 v8, v210, v211
	v_cvt_pk_bf16_f32 v9, v212, v213
	v_cvt_pk_bf16_f32 v10, v214, v215
	v_cvt_pk_bf16_f32 v11, v216, v217
	s_waitcnt vmcnt(18)
	v_cvt_pk_f32_fp8_e32 v[202:203], v222
	v_cvt_pk_f32_fp8_sdwa v[204:205], v222 src0_sel:WORD_1
	v_cvt_pk_f32_fp8_e32 v[206:207], v223
	v_cvt_pk_f32_fp8_sdwa v[208:209], v223 src0_sel:WORD_1
	v_cvt_pk_bf16_f32 v12, v202, v203
	v_cvt_pk_bf16_f32 v13, v204, v205
	v_cvt_pk_bf16_f32 v14, v206, v207
	v_cvt_pk_bf16_f32 v15, v208, v209
	s_waitcnt vmcnt(17)
	v_cvt_pk_f32_fp8_e32 v[210:211], v224
	v_cvt_pk_f32_fp8_sdwa v[212:213], v224 src0_sel:WORD_1
	v_cvt_pk_f32_fp8_e32 v[214:215], v225
	v_cvt_pk_f32_fp8_sdwa v[216:217], v225 src0_sel:WORD_1
	v_cvt_pk_bf16_f32 v16, v210, v211
	v_cvt_pk_bf16_f32 v17, v212, v213
	v_cvt_pk_bf16_f32 v18, v214, v215
	v_cvt_pk_bf16_f32 v19, v216, v217
	s_waitcnt vmcnt(16)
	v_cvt_pk_f32_fp8_e32 v[202:203], v226
	v_cvt_pk_f32_fp8_sdwa v[204:205], v226 src0_sel:WORD_1
	v_cvt_pk_f32_fp8_e32 v[206:207], v227
	v_cvt_pk_f32_fp8_sdwa v[208:209], v227 src0_sel:WORD_1
	v_cvt_pk_bf16_f32 v20, v202, v203
	v_cvt_pk_bf16_f32 v21, v204, v205
	v_cvt_pk_bf16_f32 v22, v206, v207
	v_cvt_pk_bf16_f32 v23, v208, v209
	s_waitcnt vmcnt(15)
	v_cvt_pk_f32_fp8_e32 v[210:211], v228
	v_cvt_pk_f32_fp8_sdwa v[212:213], v228 src0_sel:WORD_1
	v_cvt_pk_f32_fp8_e32 v[214:215], v229
	v_cvt_pk_f32_fp8_sdwa v[216:217], v229 src0_sel:WORD_1
	v_cvt_pk_bf16_f32 v24, v210, v211
	v_cvt_pk_bf16_f32 v25, v212, v213
	v_cvt_pk_bf16_f32 v26, v214, v215
	v_cvt_pk_bf16_f32 v27, v216, v217
	s_waitcnt vmcnt(14)
	v_cvt_pk_f32_fp8_e32 v[202:203], v230
	v_cvt_pk_f32_fp8_sdwa v[204:205], v230 src0_sel:WORD_1
	v_cvt_pk_f32_fp8_e32 v[206:207], v231
	v_cvt_pk_f32_fp8_sdwa v[208:209], v231 src0_sel:WORD_1
	v_cvt_pk_bf16_f32 v28, v202, v203
	v_cvt_pk_bf16_f32 v29, v204, v205
	v_cvt_pk_bf16_f32 v30, v206, v207
	v_cvt_pk_bf16_f32 v31, v208, v209
	s_waitcnt vmcnt(13)
	v_cvt_pk_f32_fp8_e32 v[210:211], v232
	v_cvt_pk_f32_fp8_sdwa v[212:213], v232 src0_sel:WORD_1
	v_cvt_pk_f32_fp8_e32 v[214:215], v233
	v_cvt_pk_f32_fp8_sdwa v[216:217], v233 src0_sel:WORD_1
	v_cvt_pk_bf16_f32 v32, v210, v211
	v_cvt_pk_bf16_f32 v33, v212, v213
	v_cvt_pk_bf16_f32 v34, v214, v215
	v_cvt_pk_bf16_f32 v35, v216, v217
	s_and_b32 s14, s10, 0x7fc
	s_cmp_lt_u32 s14, 29
	s_waitcnt vmcnt(8)
	ds_write_b128 v170, v[44:47]
	s_waitcnt vmcnt(7)
	ds_write_b128 v170, v[48:51] offset:544
	s_waitcnt vmcnt(6)
	ds_write_b128 v170, v[60:63] offset:1088
	s_waitcnt vmcnt(5)
	ds_write_b128 v170, v[68:71] offset:1632
	s_waitcnt vmcnt(4)
	ds_write_b128 v170, v[84:87] offset:2176
	s_waitcnt vmcnt(3)
	ds_write_b128 v170, v[88:91] offset:2720
	s_waitcnt vmcnt(2)
	ds_write_b128 v170, v[100:103] offset:3264
	s_waitcnt vmcnt(1)
	ds_write_b128 v170, v[108:111] offset:3808
	s_cbranch_scc1 .LBB0_998
; #define P4_LOAD(ch) do { const u32x4 kk_ = *(const LAS u32x4*)(idxs + tok * 256 + (ch) * 32 + wrow); \
;       _Pragma("unroll") for (int i = 0; i < 8; ++i) { \
;       const int key = (int)((kk_[i >> 1] >> (16 * (i & 1))) & 0xffffu); stg[i] = *(const u32x4*)(cbase + (size_t)key * 256); } } while (0)
; #define P4_WRITE(bufp) do { _Pragma("unroll") for (int i = 0; i < 8; ++i) \
;       *(LAS u32x4*)((bufp) + (wrow + i) * CROW + 16 * (wch ^ (lane >> 5))) = stg[i]; } while (0)
; __device__ __forceinline__ void p4_attn(const Params& p, unsigned char* lds, int bid, int nb, bool dry) {
;     ...
;     P4_LOAD(0);
;     P4_WRITE(cbuf + tok * CTOK);
;     if (nch > 1) P4_LOAD(1);
	ds_read_b128 v[36:39], v167 offset:64
	s_waitcnt lgkmcnt(0)
	v_lshlrev_b32_sdwa v0, v171, v36 dst_sel:DWORD dst_unused:UNUSED_PAD src0_sel:DWORD src1_sel:WORD_0
	v_lshlrev_b32_sdwa v2, v171, v36 dst_sel:DWORD dst_unused:UNUSED_PAD src0_sel:DWORD src1_sel:WORD_1
	v_add3_u32 v0, v0, v156, s42
	v_add3_u32 v2, v2, v156, s42
	global_load_dwordx4 v[202:205], v0, s[40:41]
	global_load_dwordx4 v[206:209], v2, s[40:41]
	v_lshlrev_b32_sdwa v0, v171, v37 dst_sel:DWORD dst_unused:UNUSED_PAD src0_sel:DWORD src1_sel:WORD_0
	v_lshlrev_b32_sdwa v2, v171, v37 dst_sel:DWORD dst_unused:UNUSED_PAD src0_sel:DWORD src1_sel:WORD_1
	v_add3_u32 v0, v0, v156, s42
	v_add3_u32 v2, v2, v156, s42
	global_load_dwordx4 v[210:213], v0, s[40:41]
	global_load_dwordx4 v[214:217], v2, s[40:41]
	v_lshlrev_b32_sdwa v0, v171, v38 dst_sel:DWORD dst_unused:UNUSED_PAD src0_sel:DWORD src1_sel:WORD_0
	v_lshlrev_b32_sdwa v2, v171, v38 dst_sel:DWORD dst_unused:UNUSED_PAD src0_sel:DWORD src1_sel:WORD_1
	v_add3_u32 v0, v0, v156, s42
	v_add3_u32 v2, v2, v156, s42
	global_load_dwordx4 v[218:221], v0, s[40:41]
	global_load_dwordx4 v[222:225], v2, s[40:41]
	v_lshlrev_b32_sdwa v0, v171, v39 dst_sel:DWORD dst_unused:UNUSED_PAD src0_sel:DWORD src1_sel:WORD_0
	v_lshlrev_b32_sdwa v2, v171, v39 dst_sel:DWORD dst_unused:UNUSED_PAD src0_sel:DWORD src1_sel:WORD_1
	v_add3_u32 v0, v0, v156, s42
	v_add3_u32 v2, v2, v156, s42
	global_load_dwordx4 v[226:229], v0, s[40:41]
	global_load_dwordx4 v[230:233], v2, s[40:41]
	s_cmp_lt_u32 s14, 61
	s_cbranch_scc1 .LBB0_998
	ds_read_b128 v[36:39], v167 offset:128
	s_waitcnt lgkmcnt(0)
	v_lshlrev_b32_sdwa v0, v171, v36 dst_sel:DWORD dst_unused:UNUSED_PAD src0_sel:DWORD src1_sel:WORD_0
	v_lshlrev_b32_sdwa v2, v171, v36 dst_sel:DWORD dst_unused:UNUSED_PAD src0_sel:DWORD src1_sel:WORD_1
	v_add3_u32 v0, v0, v156, s42
	v_add3_u32 v2, v2, v156, s42
	global_load_dwordx4 v[44:47], v0, s[40:41]
	global_load_dwordx4 v[48:51], v2, s[40:41]
	v_lshlrev_b32_sdwa v0, v171, v37 dst_sel:DWORD dst_unused:UNUSED_PAD src0_sel:DWORD src1_sel:WORD_0
	v_lshlrev_b32_sdwa v2, v171, v37 dst_sel:DWORD dst_unused:UNUSED_PAD src0_sel:DWORD src1_sel:WORD_1
	v_add3_u32 v0, v0, v156, s42
	v_add3_u32 v2, v2, v156, s42
	global_load_dwordx4 v[60:63], v0, s[40:41]
	global_load_dwordx4 v[68:71], v2, s[40:41]
	v_lshlrev_b32_sdwa v0, v171, v38 dst_sel:DWORD dst_unused:UNUSED_PAD src0_sel:DWORD src1_sel:WORD_0
	v_lshlrev_b32_sdwa v2, v171, v38 dst_sel:DWORD dst_unused:UNUSED_PAD src0_sel:DWORD src1_sel:WORD_1
	v_add3_u32 v0, v0, v156, s42
	v_add3_u32 v2, v2, v156, s42
	global_load_dwordx4 v[84:87], v0, s[40:41]
	global_load_dwordx4 v[88:91], v2, s[40:41]
	v_lshlrev_b32_sdwa v0, v171, v39 dst_sel:DWORD dst_unused:UNUSED_PAD src0_sel:DWORD src1_sel:WORD_0
	v_lshlrev_b32_sdwa v2, v171, v39 dst_sel:DWORD dst_unused:UNUSED_PAD src0_sel:DWORD src1_sel:WORD_1
	v_add3_u32 v0, v0, v156, s42
	v_add3_u32 v2, v2, v156, s42
	global_load_dwordx4 v[100:103], v0, s[40:41]
	global_load_dwordx4 v[108:111], v2, s[40:41]

; #define LAS __attribute__((address_space(3)))
; #define P4_LOAD(ch) do { const u32x4 kk_ = *(const LAS u32x4*)(idxs + tok * 256 + (ch) * 32 + wrow); \
;       _Pragma("unroll") for (int i = 0; i < 8; ++i) { \
;       const int key = (int)((kk_[i >> 1] >> (16 * (i & 1))) & 0xffffu); stg[i] = *(const u32x4*)(cbase + (size_t)key * 256); } } while (0)
; #define P4_WRITE(bufp) do { _Pragma("unroll") for (int i = 0; i < 8; ++i) \
;       *(LAS u32x4*)((bufp) + (wrow + i) * CROW + 16 * (wch ^ (lane >> 5))) = stg[i]; } while (0)
; __device__ __forceinline__ void p4_attn(const Params& p, unsigned char* lds, int bid, int nb, bool dry) {
;     ...
;     for (int ch = 0; ch < nch; ++ch) {
;       LAS unsigned char* cb = cbuf + (ch & 1) * CBUF + tok * CTOK;
;       if (ch + 1 < nch) { P4_WRITE(cbuf + ((ch + 1) & 1) * CBUF + tok * CTOK); if (ch + 2 < nch) P4_LOAD(ch + 2); }
;       f32x4 s0 = (f32x4){0.f, 0.f, 0.f, 0.f}, s1 = (f32x4){0.f, 0.f, 0.f, 0.f};
; #pragma unroll
;       for (int s = 0; s < 8; ++s) {
;         const bf16x8 a0 = *(const LAS bf16x8*)(cb + r16 * CROW + s * 64 + qoff);
;         const bf16x8 a1 = *(const LAS bf16x8*)(cb + (16 + r16) * CROW + s * 64 + qoff);
;         s0 = __builtin_amdgcn_mfma_f32_16x16x32_bf16(a0, qB[s], s0, 0, 0, 0);
;         s1 = __builtin_amdgcn_mfma_f32_16x16x32_bf16(a1, qB[s], s1, 0, 0, 0);
;       }
.LBB0_1005:
	s_add_i32 s27, s10, 2
	s_cmp_ge_u32 s27, s21
	s_cbranch_scc1 .Lp4_w1
	s_bitcmp1_b32 s10, 0
	s_cbranch_scc1 .Lp4_w2_odd
	s_bitcmp1_b32 s10, 0
	s_cselect_b32 s11, 0x11000, 0
	s_add_i32 s12, s5, s11
	s_lshl_b32 s13, s10, 5
	v_add3_u32 v2, s12, v168, v162
	s_add_i32 s27, s10, 3
	v_lshl_add_u32 v3, s27, 6, v167
	ds_read_b128 v[196:199], v3
	ds_read_b128 v[234:237], v2
	ds_read_b128 v[238:241], v2 offset:8704
	ds_read_b128 v[242:245], v2 offset:64
	ds_read_b128 v[246:249], v2 offset:8768
	ds_read_b128 v[250:253], v2 offset:128
	ds_read_b128 v[188:191], v2 offset:8832
	v_or_b32_e32 v0, s13, v148
	v_lshl_add_u32 v3, v0, 1, s3
	s_bitcmp1_b32 s23, 0
	s_cselect_b32 s11, 0x11000, 0
	v_add_u32_e32 v201, s11, v170
	s_waitcnt lgkmcnt(5)
	v_mfma_f32_16x16x32_bf16 v[140:143], v[234:237], v[4:7], 0
	ds_read_b128 v[234:237], v2 offset:192
	s_waitcnt lgkmcnt(5)
	v_mfma_f32_16x16x32_bf16 v[144:147], v[238:241], v[4:7], 0
	ds_read_b128 v[238:241], v2 offset:8896
	ds_read2_b64 v[184:187], v3 offset1:4
	s_waitcnt lgkmcnt(6)
	v_mfma_f32_16x16x32_bf16 v[140:143], v[242:245], v[8:11], v[140:143]
	ds_read_b128 v[242:245], v2 offset:256
	s_waitcnt vmcnt(15)
	ds_write_b128 v201, v[202:205]
	s_waitcnt lgkmcnt(7)
	v_mfma_f32_16x16x32_bf16 v[144:147], v[246:249], v[8:11], v[144:147]
	ds_read_b128 v[246:249], v2 offset:8960
	s_waitcnt vmcnt(14)
	ds_write_b128 v201, v[206:209] offset:544
	s_waitcnt lgkmcnt(8)
	v_mfma_f32_16x16x32_bf16 v[140:143], v[250:253], v[12:15], v[140:143]
	ds_read_b128 v[250:253], v2 offset:320
	s_waitcnt vmcnt(13)
	ds_write_b128 v201, v[210:213] offset:1088
	s_waitcnt lgkmcnt(9)
	v_mfma_f32_16x16x32_bf16 v[144:147], v[188:191], v[12:15], v[144:147]
	ds_read_b128 v[188:191], v2 offset:9024
	s_waitcnt vmcnt(12)
	ds_write_b128 v201, v[214:217] offset:1632
	s_waitcnt lgkmcnt(10)
	v_mfma_f32_16x16x32_bf16 v[140:143], v[234:237], v[16:19], v[140:143]
	ds_read_b128 v[234:237], v2 offset:384
	s_waitcnt vmcnt(11)
	ds_write_b128 v201, v[218:221] offset:2176
	s_waitcnt lgkmcnt(11)
	v_mfma_f32_16x16x32_bf16 v[144:147], v[238:241], v[16:19], v[144:147]
	ds_read_b128 v[238:241], v2 offset:9088
	s_waitcnt vmcnt(10)
	ds_write_b128 v201, v[222:225] offset:2720
	s_waitcnt lgkmcnt(11)
	v_mfma_f32_16x16x32_bf16 v[140:143], v[242:245], v[20:23], v[140:143]
	ds_read_b128 v[242:245], v2 offset:448
	s_waitcnt vmcnt(9)
	ds_write_b128 v201, v[226:229] offset:3264
	s_waitcnt lgkmcnt(11)
	v_mfma_f32_16x16x32_bf16 v[144:147], v[246:249], v[20:23], v[144:147]
	ds_read_b128 v[246:249], v2 offset:9152
	s_waitcnt vmcnt(8)
	ds_write_b128 v201, v[230:233] offset:3808
	s_waitcnt lgkmcnt(11)
	v_mfma_f32_16x16x32_bf16 v[140:143], v[250:253], v[24:27], v[140:143]
	s_waitcnt lgkmcnt(9)
	v_mfma_f32_16x16x32_bf16 v[144:147], v[188:191], v[24:27], v[144:147]
	s_waitcnt lgkmcnt(7)
	v_mfma_f32_16x16x32_bf16 v[140:143], v[234:237], v[28:31], v[140:143]
	s_waitcnt lgkmcnt(5)
	v_mfma_f32_16x16x32_bf16 v[144:147], v[238:241], v[28:31], v[144:147]
	s_waitcnt lgkmcnt(3)
	v_mfma_f32_16x16x32_bf16 v[140:143], v[242:245], v[32:35], v[140:143]
	s_waitcnt lgkmcnt(1)
	v_mfma_f32_16x16x32_bf16 v[144:147], v[246:249], v[32:35], v[144:147]
	s_add_i32 s27, s10, 3
	s_cmp_ge_u32 s27, s21
	s_cbranch_scc1 .Lp4_softmax
	s_waitcnt lgkmcnt(0)
	v_lshlrev_b32_sdwa v0, v171, v196 dst_sel:DWORD dst_unused:UNUSED_PAD src0_sel:DWORD src1_sel:WORD_0
	v_lshlrev_b32_sdwa v2, v171, v196 dst_sel:DWORD dst_unused:UNUSED_PAD src0_sel:DWORD src1_sel:WORD_1
	v_add3_u32 v0, v0, v156, s42
	v_add3_u32 v2, v2, v156, s42
	global_load_dwordx4 v[202:205], v0, s[40:41]
	global_load_dwordx4 v[206:209], v2, s[40:41]
	v_lshlrev_b32_sdwa v0, v171, v197 dst_sel:DWORD dst_unused:UNUSED_PAD src0_sel:DWORD src1_sel:WORD_0
	v_lshlrev_b32_sdwa v2, v171, v197 dst_sel:DWORD dst_unused:UNUSED_PAD src0_sel:DWORD src1_sel:WORD_1
	v_add3_u32 v0, v0, v156, s42
	v_add3_u32 v2, v2, v156, s42
	global_load_dwordx4 v[210:213], v0, s[40:41]
	global_load_dwordx4 v[214:217], v2, s[40:41]
	v_lshlrev_b32_sdwa v0, v171, v198 dst_sel:DWORD dst_unused:UNUSED_PAD src0_sel:DWORD src1_sel:WORD_0
	v_lshlrev_b32_sdwa v2, v171, v198 dst_sel:DWORD dst_unused:UNUSED_PAD src0_sel:DWORD src1_sel:WORD_1
	v_add3_u32 v0, v0, v156, s42
	v_add3_u32 v2, v2, v156, s42
	global_load_dwordx4 v[218:221], v0, s[40:41]
	global_load_dwordx4 v[222:225], v2, s[40:41]
	v_lshlrev_b32_sdwa v0, v171, v199 dst_sel:DWORD dst_unused:UNUSED_PAD src0_sel:DWORD src1_sel:WORD_0
	v_lshlrev_b32_sdwa v2, v171, v199 dst_sel:DWORD dst_unused:UNUSED_PAD src0_sel:DWORD src1_sel:WORD_1
	v_add3_u32 v0, v0, v156, s42
	v_add3_u32 v2, v2, v156, s42
	global_load_dwordx4 v[226:229], v0, s[40:41]
	global_load_dwordx4 v[230:233], v2, s[40:41]
	s_branch .Lp4_softmax
; #define LAS __attribute__((address_space(3)))
; #define P4_LOAD(ch) do { const u32x4 kk_ = *(const LAS u32x4*)(idxs + tok * 256 + (ch) * 32 + wrow); \
;       _Pragma("unroll") for (int i = 0; i < 8; ++i) { \
;       const int key = (int)((kk_[i >> 1] >> (16 * (i & 1))) & 0xffffu); stg[i] = *(const u32x4*)(cbase + (size_t)key * 256); } } while (0)
; #define P4_WRITE(bufp) do { _Pragma("unroll") for (int i = 0; i < 8; ++i) \
;       *(LAS u32x4*)((bufp) + (wrow + i) * CROW + 16 * (wch ^ (lane >> 5))) = stg[i]; } while (0)
; __device__ __forceinline__ void p4_attn(const Params& p, unsigned char* lds, int bid, int nb, bool dry) {
;     ...
;     for (int ch = 0; ch < nch; ++ch) {
;       LAS unsigned char* cb = cbuf + (ch & 1) * CBUF + tok * CTOK;
;       if (ch + 1 < nch) { P4_WRITE(cbuf + ((ch + 1) & 1) * CBUF + tok * CTOK); if (ch + 2 < nch) P4_LOAD(ch + 2); }
;       f32x4 s0 = (f32x4){0.f, 0.f, 0.f, 0.f}, s1 = (f32x4){0.f, 0.f, 0.f, 0.f};
; #pragma unroll
;       for (int s = 0; s < 8; ++s) {
;         const bf16x8 a0 = *(const LAS bf16x8*)(cb + r16 * CROW + s * 64 + qoff);
;         const bf16x8 a1 = *(const LAS bf16x8*)(cb + (16 + r16) * CROW + s * 64 + qoff);
;         s0 = __builtin_amdgcn_mfma_f32_16x16x32_bf16(a0, qB[s], s0, 0, 0, 0);
;         s1 = __builtin_amdgcn_mfma_f32_16x16x32_bf16(a1, qB[s], s1, 0, 0, 0);
;       }
.Lp4_w2_odd:
	s_bitcmp1_b32 s10, 0
	s_cselect_b32 s11, 0x11000, 0
	s_add_i32 s12, s5, s11
	s_lshl_b32 s13, s10, 5
	v_add3_u32 v2, s12, v168, v162
	s_add_i32 s27, s10, 3
	v_lshl_add_u32 v3, s27, 6, v167
	ds_read_b128 v[196:199], v3
	ds_read_b128 v[234:237], v2
	ds_read_b128 v[238:241], v2 offset:8704
	ds_read_b128 v[242:245], v2 offset:64
	ds_read_b128 v[246:249], v2 offset:8768
	ds_read_b128 v[250:253], v2 offset:128
	ds_read_b128 v[188:191], v2 offset:8832
	v_or_b32_e32 v0, s13, v148
	v_lshl_add_u32 v3, v0, 1, s3
	s_bitcmp1_b32 s23, 0
	s_cselect_b32 s11, 0x11000, 0
	v_add_u32_e32 v201, s11, v170
	s_waitcnt lgkmcnt(5)
	v_mfma_f32_16x16x32_bf16 v[140:143], v[234:237], v[4:7], 0
	ds_read_b128 v[234:237], v2 offset:192
	s_waitcnt lgkmcnt(5)
	v_mfma_f32_16x16x32_bf16 v[144:147], v[238:241], v[4:7], 0
	ds_read_b128 v[238:241], v2 offset:8896
	ds_read2_b64 v[184:187], v3 offset1:4
	s_waitcnt lgkmcnt(6)
	v_mfma_f32_16x16x32_bf16 v[140:143], v[242:245], v[8:11], v[140:143]
	ds_read_b128 v[242:245], v2 offset:256
	s_waitcnt vmcnt(15)
	ds_write_b128 v201, v[44:47]
	s_waitcnt lgkmcnt(7)
	v_mfma_f32_16x16x32_bf16 v[144:147], v[246:249], v[8:11], v[144:147]
	ds_read_b128 v[246:249], v2 offset:8960
	s_waitcnt vmcnt(14)
	ds_write_b128 v201, v[48:51] offset:544
	s_waitcnt lgkmcnt(8)
	v_mfma_f32_16x16x32_bf16 v[140:143], v[250:253], v[12:15], v[140:143]
	ds_read_b128 v[250:253], v2 offset:320
	s_waitcnt vmcnt(13)
	ds_write_b128 v201, v[60:63] offset:1088
	s_waitcnt lgkmcnt(9)
	v_mfma_f32_16x16x32_bf16 v[144:147], v[188:191], v[12:15], v[144:147]
	ds_read_b128 v[188:191], v2 offset:9024
	s_waitcnt vmcnt(12)
	ds_write_b128 v201, v[68:71] offset:1632
	s_waitcnt lgkmcnt(10)
	v_mfma_f32_16x16x32_bf16 v[140:143], v[234:237], v[16:19], v[140:143]
	ds_read_b128 v[234:237], v2 offset:384
	s_waitcnt vmcnt(11)
	ds_write_b128 v201, v[84:87] offset:2176
	s_waitcnt lgkmcnt(11)
	v_mfma_f32_16x16x32_bf16 v[144:147], v[238:241], v[16:19], v[144:147]
	ds_read_b128 v[238:241], v2 offset:9088
	s_waitcnt vmcnt(10)
	ds_write_b128 v201, v[88:91] offset:2720
	s_waitcnt lgkmcnt(11)
	v_mfma_f32_16x16x32_bf16 v[140:143], v[242:245], v[20:23], v[140:143]
	ds_read_b128 v[242:245], v2 offset:448
	s_waitcnt vmcnt(9)
	ds_write_b128 v201, v[100:103] offset:3264
	s_waitcnt lgkmcnt(11)
	v_mfma_f32_16x16x32_bf16 v[144:147], v[246:249], v[20:23], v[144:147]
	ds_read_b128 v[246:249], v2 offset:9152
	s_waitcnt vmcnt(8)
	ds_write_b128 v201, v[108:111] offset:3808
	s_waitcnt lgkmcnt(11)
	v_mfma_f32_16x16x32_bf16 v[140:143], v[250:253], v[24:27], v[140:143]
	s_waitcnt lgkmcnt(9)
	v_mfma_f32_16x16x32_bf16 v[144:147], v[188:191], v[24:27], v[144:147]
	s_waitcnt lgkmcnt(7)
	v_mfma_f32_16x16x32_bf16 v[140:143], v[234:237], v[28:31], v[140:143]
	s_waitcnt lgkmcnt(5)
	v_mfma_f32_16x16x32_bf16 v[144:147], v[238:241], v[28:31], v[144:147]
	s_waitcnt lgkmcnt(3)
	v_mfma_f32_16x16x32_bf16 v[140:143], v[242:245], v[32:35], v[140:143]
	s_waitcnt lgkmcnt(1)
	v_mfma_f32_16x16x32_bf16 v[144:147], v[246:249], v[32:35], v[144:147]
	s_add_i32 s27, s10, 3
	s_cmp_ge_u32 s27, s21
	s_cbranch_scc1 .Lp4_softmax
	s_waitcnt lgkmcnt(0)
	v_lshlrev_b32_sdwa v0, v171, v196 dst_sel:DWORD dst_unused:UNUSED_PAD src0_sel:DWORD src1_sel:WORD_0
	v_lshlrev_b32_sdwa v2, v171, v196 dst_sel:DWORD dst_unused:UNUSED_PAD src0_sel:DWORD src1_sel:WORD_1
	v_add3_u32 v0, v0, v156, s42
	v_add3_u32 v2, v2, v156, s42
	global_load_dwordx4 v[44:47], v0, s[40:41]
	global_load_dwordx4 v[48:51], v2, s[40:41]
	v_lshlrev_b32_sdwa v0, v171, v197 dst_sel:DWORD dst_unused:UNUSED_PAD src0_sel:DWORD src1_sel:WORD_0
	v_lshlrev_b32_sdwa v2, v171, v197 dst_sel:DWORD dst_unused:UNUSED_PAD src0_sel:DWORD src1_sel:WORD_1
	v_add3_u32 v0, v0, v156, s42
	v_add3_u32 v2, v2, v156, s42
	global_load_dwordx4 v[60:63], v0, s[40:41]
	global_load_dwordx4 v[68:71], v2, s[40:41]
	v_lshlrev_b32_sdwa v0, v171, v198 dst_sel:DWORD dst_unused:UNUSED_PAD src0_sel:DWORD src1_sel:WORD_0
	v_lshlrev_b32_sdwa v2, v171, v198 dst_sel:DWORD dst_unused:UNUSED_PAD src0_sel:DWORD src1_sel:WORD_1
	v_add3_u32 v0, v0, v156, s42
	v_add3_u32 v2, v2, v156, s42
	global_load_dwordx4 v[84:87], v0, s[40:41]
	global_load_dwordx4 v[88:91], v2, s[40:41]
	v_lshlrev_b32_sdwa v0, v171, v199 dst_sel:DWORD dst_unused:UNUSED_PAD src0_sel:DWORD src1_sel:WORD_0
	v_lshlrev_b32_sdwa v2, v171, v199 dst_sel:DWORD dst_unused:UNUSED_PAD src0_sel:DWORD src1_sel:WORD_1
	v_add3_u32 v0, v0, v156, s42
	v_add3_u32 v2, v2, v156, s42
	global_load_dwordx4 v[100:103], v0, s[40:41]
	global_load_dwordx4 v[108:111], v2, s[40:41]
	s_branch .Lp4_softmax
